# plus grid barrier: every workgroup starts an L2 write-back on arrival (not waited), shortening the last arriver's release
# baseline (speedup 1.0000x reference)
; DEV unsigned xb_add(unsigned* p, unsigned v) { return __hip_atomic_fetch_add(p, v, __ATOMIC_RELAXED, __HIP_MEMORY_SCOPE_AGENT); }
; DEV void xcd_barrier(const XcdBarrier& b) {
;     asm volatile("s_waitcnt vmcnt(0)" ::: "memory");
;     __syncthreads();
;     if (threadIdx.x == 0) {
;         unsigned* bar = b.bar;
;         __builtin_amdgcn_s_waitcnt(0);
;         unsigned nloc = b.st[0], nx = b.st[1];
;         if (nloc == 0u) { xcd_barrier_complete(bar, b.x, nloc, nx); b.st[0] = nloc; b.st[1] = nx; }
;         const unsigned old = xb_add(&bar[XB_XSUB(b.x)], 1u);
;         const unsigned gen = old / nloc;
;         if (old + 1u == (gen + 1u) * nloc) {
;             __builtin_amdgcn_fence(__ATOMIC_RELEASE, "agent");
;             asm volatile("s_waitcnt vmcnt(0)" ::: "memory");
;             const unsigned og = xb_add(&bar[XB_TOP], 1u);
;             const unsigned tg = og / nx;
;             if (og + 1u == (tg + 1u) * nx) xb_add(&bar[XB_TOPGEN], 1u);
.LBB0_134:
	s_mov_b64 s[8:9], exec
	s_lshl_b32 s6, s3, 8
	v_mbcnt_lo_u32_b32 v2, s8, 0
	s_add_u32 s6, s28, s6
	v_mbcnt_hi_u32_b32 v2, s9, v2
	s_addc_u32 s7, s29, 0
	v_cmp_eq_u32_e32 vcc, 0, v2
	s_and_saveexec_b64 s[10:11], vcc
	s_cbranch_execz .LBB0_136
	s_bcnt1_i32_b64 s8, s[8:9]
	v_mov_b32_e32 v4, 0x1000
	v_mov_b32_e32 v5, s8
	buffer_wbl2 sc1
	global_atomic_add v4, v4, v5, s[6:7] offset:1024 sc0

; DEV unsigned xb_add(unsigned* p, unsigned v) { return __hip_atomic_fetch_add(p, v, __ATOMIC_RELAXED, __HIP_MEMORY_SCOPE_AGENT); }
; DEV void xcd_barrier(const XcdBarrier& b) {
;     asm volatile("s_waitcnt vmcnt(0)" ::: "memory");
;     __syncthreads();
;     if (threadIdx.x == 0) {
;         unsigned* bar = b.bar;
;         __builtin_amdgcn_s_waitcnt(0);
;         unsigned nloc = b.st[0], nx = b.st[1];
;         if (nloc == 0u) { xcd_barrier_complete(bar, b.x, nloc, nx); b.st[0] = nloc; b.st[1] = nx; }
;         const unsigned old = xb_add(&bar[XB_XSUB(b.x)], 1u);
;         const unsigned gen = old / nloc;
;         if (old + 1u == (gen + 1u) * nloc) {
;             __builtin_amdgcn_fence(__ATOMIC_RELEASE, "agent");
;             asm volatile("s_waitcnt vmcnt(0)" ::: "memory");
;             const unsigned og = xb_add(&bar[XB_TOP], 1u);
;             const unsigned tg = og / nx;
;             if (og + 1u == (tg + 1u) * nx) xb_add(&bar[XB_TOPGEN], 1u);
.LBB0_1503:
	s_mov_b64 s[8:9], exec
	s_lshl_b32 s3, s3, 8
	v_mbcnt_lo_u32_b32 v2, s8, 0
	s_add_u32 s6, s28, s3
	v_mbcnt_hi_u32_b32 v2, s9, v2
	s_addc_u32 s7, s29, 0
	v_cmp_eq_u32_e32 vcc, 0, v2
	s_and_saveexec_b64 s[10:11], vcc
	s_cbranch_execz .LBB0_1505
	s_bcnt1_i32_b64 s3, s[8:9]
	v_mov_b32_e32 v4, 0x1000
	v_mov_b32_e32 v5, s3
	buffer_wbl2 sc1
	global_atomic_add v4, v4, v5, s[6:7] offset:1024 sc0
